# grid barrier followers invalidate only their L1 (buffer_inv sc0); the XCD leader's L2 invalidate completes before it releases them
# speedup vs baseline: 1.0346x; 1.0120x over previous
.LBB0_38:
	s_or_b64 exec, exec, s[10:11]
	s_waitcnt vmcnt(0)
	buffer_inv sc0
	s_waitcnt vmcnt(0)

.LBB0_56:
	s_or_b64 exec, exec, s[8:9]
	s_mov_b64 s[8:9], exec
	v_mbcnt_lo_u32_b32 v1, s8, 0
	v_mbcnt_hi_u32_b32 v1, s9, v1
	v_cmp_eq_u32_e32 vcc, 0, v1
	s_waitcnt vmcnt(0)
	buffer_inv sc1
	s_waitcnt vmcnt(0)
	s_and_saveexec_b64 s[10:11], vcc
	s_cbranch_execz .LBB0_58
	s_bcnt1_i32_b64 s8, s[8:9]
	v_mov_b32_e32 v1, 0x2000
	v_mov_b32_e32 v2, s8
	global_atomic_add v1, v2, s[2:3] offset:1024

.LBB0_157:
	s_or_b64 exec, exec, s[12:13]
	s_waitcnt vmcnt(0)
	buffer_inv sc0
	s_waitcnt vmcnt(0)

.LBB0_175:
	s_or_b64 exec, exec, s[4:5]
	s_mov_b64 s[4:5], exec
	v_mbcnt_lo_u32_b32 v1, s4, 0
	v_mbcnt_hi_u32_b32 v1, s5, v1
	v_cmp_eq_u32_e32 vcc, 0, v1
	s_waitcnt vmcnt(0)
	buffer_inv sc1
	s_waitcnt vmcnt(0)
	s_and_saveexec_b64 s[10:11], vcc
	s_cbranch_execz .LBB0_177
	s_bcnt1_i32_b64 s4, s[4:5]
	v_mov_b32_e32 v1, 0
	v_mov_b32_e32 v2, s4
	global_atomic_add v1, v2, s[8:9]

.LBB0_427:
	s_or_b64 exec, exec, s[2:3]
	s_mov_b64 s[2:3], exec
	v_mbcnt_lo_u32_b32 v1, s2, 0
	v_mbcnt_hi_u32_b32 v1, s3, v1
	v_cmp_eq_u32_e32 vcc, 0, v1
	s_waitcnt vmcnt(0)
	buffer_inv sc1
	s_waitcnt vmcnt(0)
	s_and_saveexec_b64 s[8:9], vcc
	s_cbranch_execz .LBB0_429
	s_bcnt1_i32_b64 s2, s[2:3]
	v_mov_b32_e32 v1, 0
	v_mov_b32_e32 v2, s2
	global_atomic_add v1, v2, s[4:5]

.LBB0_547:
	s_or_b64 exec, exec, s[6:7]
	s_waitcnt vmcnt(0)
	buffer_inv sc0
	s_waitcnt vmcnt(0)

.LBB0_565:
	s_or_b64 exec, exec, s[4:5]
	s_mov_b64 s[4:5], exec
	v_mbcnt_lo_u32_b32 v1, s4, 0
	v_mbcnt_hi_u32_b32 v1, s5, v1
	v_cmp_eq_u32_e32 vcc, 0, v1
	s_waitcnt vmcnt(0)
	buffer_inv sc1
	s_waitcnt vmcnt(0)
	s_and_saveexec_b64 s[6:7], vcc
	s_cbranch_execz .LBB0_567
	s_bcnt1_i32_b64 s4, s[4:5]
	v_mov_b32_e32 v1, 0x2000
	v_mov_b32_e32 v2, s4
	global_atomic_add v1, v2, s[2:3] offset:1024

.LBB0_694:
	s_or_b64 exec, exec, s[8:9]
	s_waitcnt vmcnt(0)
	buffer_inv sc0
	s_waitcnt vmcnt(0)

.LBB0_712:
	s_or_b64 exec, exec, s[6:7]
	s_mov_b64 s[6:7], exec
	v_mbcnt_lo_u32_b32 v1, s6, 0
	v_mbcnt_hi_u32_b32 v1, s7, v1
	v_cmp_eq_u32_e32 vcc, 0, v1
	s_waitcnt vmcnt(0)
	buffer_inv sc1
	s_waitcnt vmcnt(0)
	s_and_saveexec_b64 s[8:9], vcc
	s_cbranch_execz .LBB0_714
	s_bcnt1_i32_b64 s6, s[6:7]
	v_mov_b32_e32 v1, 0x2000
	v_mov_b32_e32 v2, s6
	global_atomic_add v1, v2, s[4:5] offset:1024

.LBB0_807:
	s_or_b64 exec, exec, s[4:5]
	s_mov_b64 s[4:5], exec
	v_mbcnt_lo_u32_b32 v1, s4, 0
	v_mbcnt_hi_u32_b32 v1, s5, v1
	v_cmp_eq_u32_e32 vcc, 0, v1
	s_waitcnt vmcnt(0)
	buffer_inv sc1
	s_waitcnt vmcnt(0)
	s_and_saveexec_b64 s[8:9], vcc
	s_cbranch_execz .LBB0_809
	s_bcnt1_i32_b64 s4, s[4:5]
	v_mov_b32_e32 v1, 0x2000
	v_mov_b32_e32 v2, s4
	global_atomic_add v1, v2, s[2:3] offset:1024
